# P7 (w_o + gated residual) epilogue rewritten: 4 residual vectors in flight with counted vmcnt instead of 32 dependent load/store round trips
# speedup vs baseline: 1.0107x; 1.0001x over previous
.LBB0_850:
	ds_read_b128 v[140:143], v147
	ds_read_b128 v[150:153], v147 offset:1024
	ds_read_b128 v[154:157], v147 offset:2048
	ds_read_b128 v[158:161], v147 offset:3072
	s_add_u32 s76, s74, 0x100
	s_addc_u32 s77, s75, 0
	s_cmp_eq_u32 s73, 28
	s_cselect_b32 s5, s0, s77
	s_cselect_b32 s4, s1, s76
	s_cselect_b32 s51, s46, s67
	s_cselect_b32 s50, s47, s61
	v_lshl_add_u64 v[194:195], s[74:75], 0, v[132:133]
	s_add_i32 m0, s23, 0xc000
	ds_read_b128 v[162:165], v148
	ds_read_b128 v[166:169], v148 offset:1024
	ds_read_b128 v[170:173], v148 offset:2048
	ds_read_b128 v[174:177], v148 offset:3072
	ds_read_b128 v[178:181], v148 offset:4096
	ds_read_b128 v[182:185], v148 offset:5120
	ds_read_b128 v[186:189], v148 offset:6144
	ds_read_b128 v[190:193], v148 offset:7168
	global_load_lds_dwordx4 v[194:195], off
	v_lshl_add_u64 v[194:195], s[74:75], 0, v[134:135]
	s_add_i32 m0, s23, 0xe000
	s_nop 0
	global_load_lds_dwordx4 v[194:195], off
	s_waitcnt lgkmcnt(8)
	s_barrier
	s_waitcnt lgkmcnt(0)
	s_setprio 1
	s_waitcnt lgkmcnt(0)
	v_mfma_f32_16x16x32_bf16 v[124:127], v[140:143], v[162:165], v[124:127]
	v_mfma_f32_16x16x32_bf16 v[100:103], v[154:157], v[162:165], v[100:103]
	v_mfma_f32_16x16x32_bf16 v[120:123], v[140:143], v[170:173], v[120:123]
	v_mfma_f32_16x16x32_bf16 v[96:99], v[154:157], v[170:173], v[96:99]
	v_mfma_f32_16x16x32_bf16 v[116:119], v[140:143], v[178:181], v[116:119]
	v_mfma_f32_16x16x32_bf16 v[88:91], v[154:157], v[178:181], v[88:91]
	v_mfma_f32_16x16x32_bf16 v[112:115], v[140:143], v[186:189], v[112:115]
	v_mfma_f32_16x16x32_bf16 v[80:83], v[154:157], v[186:189], v[80:83]
	v_mfma_f32_16x16x32_bf16 v[124:127], v[150:153], v[166:169], v[124:127]
	v_mfma_f32_16x16x32_bf16 v[100:103], v[158:161], v[166:169], v[100:103]
	v_mfma_f32_16x16x32_bf16 v[120:123], v[150:153], v[174:177], v[120:123]
	v_mfma_f32_16x16x32_bf16 v[96:99], v[158:161], v[174:177], v[96:99]
	v_mfma_f32_16x16x32_bf16 v[116:119], v[150:153], v[182:185], v[116:119]
	v_mfma_f32_16x16x32_bf16 v[88:91], v[158:161], v[182:185], v[88:91]
	v_mfma_f32_16x16x32_bf16 v[112:115], v[150:153], v[190:193], v[112:115]
	v_mfma_f32_16x16x32_bf16 v[80:83], v[158:161], v[190:193], v[80:83]
	s_setprio 0
	s_barrier
	s_add_i32 s42, s37, s21
	v_lshl_add_u64 v[210:211], s[50:51], 0, v[130:131]
	s_mov_b32 m0, s42
	ds_read_b128 v[194:197], v149
	ds_read_b128 v[198:201], v149 offset:1024
	ds_read_b128 v[202:205], v149 offset:2048
	ds_read_b128 v[206:209], v149 offset:3072
	global_load_lds_dwordx4 v[210:211], off
	v_lshl_add_u64 v[212:213], s[50:51], 0, v[128:129]
	s_add_i32 m0, s42, 0x2000
	s_nop 0
	global_load_lds_dwordx4 v[212:213], off
	s_barrier
	s_waitcnt lgkmcnt(0)
	s_setprio 1
	s_waitcnt lgkmcnt(0)
	v_mfma_f32_16x16x32_bf16 v[68:71], v[194:197], v[162:165], v[68:71]
	v_mfma_f32_16x16x32_bf16 v[40:43], v[202:205], v[162:165], v[40:43]
	v_mfma_f32_16x16x32_bf16 v[60:63], v[194:197], v[170:173], v[60:63]
	v_mfma_f32_16x16x32_bf16 v[32:35], v[202:205], v[170:173], v[32:35]
	v_mfma_f32_16x16x32_bf16 v[52:55], v[194:197], v[178:181], v[52:55]
	v_mfma_f32_16x16x32_bf16 v[24:27], v[202:205], v[178:181], v[24:27]
	v_mfma_f32_16x16x32_bf16 v[48:51], v[194:197], v[186:189], v[48:51]
	v_mfma_f32_16x16x32_bf16 v[16:19], v[202:205], v[186:189], v[16:19]
	v_mfma_f32_16x16x32_bf16 v[68:71], v[198:201], v[166:169], v[68:71]
	v_mfma_f32_16x16x32_bf16 v[40:43], v[206:209], v[166:169], v[40:43]
	v_mfma_f32_16x16x32_bf16 v[60:63], v[198:201], v[174:177], v[60:63]
	v_mfma_f32_16x16x32_bf16 v[32:35], v[206:209], v[174:177], v[32:35]
	v_mfma_f32_16x16x32_bf16 v[52:55], v[198:201], v[182:185], v[52:55]
	v_mfma_f32_16x16x32_bf16 v[24:27], v[206:209], v[182:185], v[24:27]
	v_mfma_f32_16x16x32_bf16 v[48:51], v[198:201], v[190:193], v[48:51]
	v_mfma_f32_16x16x32_bf16 v[16:19], v[206:209], v[190:193], v[16:19]
	s_setprio 0
	s_mov_b32 m0, s23
	v_lshl_add_u64 v[214:215], s[4:5], 0, v[130:131]
	s_barrier
	ds_read_b128 v[162:165], v148 offset:16384
	ds_read_b128 v[166:169], v148 offset:17408
	ds_read_b128 v[170:173], v148 offset:18432
	ds_read_b128 v[174:177], v148 offset:19456
	ds_read_b128 v[178:181], v148 offset:20480
	ds_read_b128 v[182:185], v148 offset:21504
	ds_read_b128 v[186:189], v148 offset:22528
	ds_read_b128 v[190:193], v148 offset:23552
	global_load_lds_dwordx4 v[214:215], off
	v_lshl_add_u64 v[216:217], s[4:5], 0, v[128:129]
	s_mov_b32 m0, s24
	s_nop 0
	global_load_lds_dwordx4 v[216:217], off
	s_barrier
	s_waitcnt lgkmcnt(0)
	s_setprio 1
	s_waitcnt lgkmcnt(0)
	v_mfma_f32_16x16x32_bf16 v[108:111], v[140:143], v[162:165], v[108:111]
	v_mfma_f32_16x16x32_bf16 v[76:79], v[154:157], v[162:165], v[76:79]
	v_mfma_f32_16x16x32_bf16 v[104:107], v[140:143], v[170:173], v[104:107]
	v_mfma_f32_16x16x32_bf16 v[72:75], v[154:157], v[170:173], v[72:75]
	v_mfma_f32_16x16x32_bf16 v[92:95], v[140:143], v[178:181], v[92:95]
	v_mfma_f32_16x16x32_bf16 v[64:67], v[154:157], v[178:181], v[64:67]
	v_mfma_f32_16x16x32_bf16 v[84:87], v[140:143], v[186:189], v[84:87]
	v_mfma_f32_16x16x32_bf16 v[56:59], v[154:157], v[186:189], v[56:59]
	v_mfma_f32_16x16x32_bf16 v[108:111], v[150:153], v[166:169], v[108:111]
	v_mfma_f32_16x16x32_bf16 v[76:79], v[158:161], v[166:169], v[76:79]
	v_mfma_f32_16x16x32_bf16 v[104:107], v[150:153], v[174:177], v[104:107]
	v_mfma_f32_16x16x32_bf16 v[72:75], v[158:161], v[174:177], v[72:75]
	v_mfma_f32_16x16x32_bf16 v[92:95], v[150:153], v[182:185], v[92:95]
	v_mfma_f32_16x16x32_bf16 v[64:67], v[158:161], v[182:185], v[64:67]
	v_mfma_f32_16x16x32_bf16 v[84:87], v[150:153], v[190:193], v[84:87]
	v_mfma_f32_16x16x32_bf16 v[56:59], v[158:161], v[190:193], v[56:59]
	s_setprio 0
	s_barrier
	s_add_u32 s42, s50, 0x80000
	s_addc_u32 s43, s51, 0
	s_add_i32 s44, s40, s21
	v_lshl_add_u64 v[140:141], s[42:43], 0, v[130:131]
	s_mov_b32 m0, s44
	s_nop 0
	global_load_lds_dwordx4 v[140:141], off
	v_lshl_add_u64 v[140:141], s[42:43], 0, v[128:129]
	s_add_i32 m0, s44, 0x2000
	s_nop 0
	global_load_lds_dwordx4 v[140:141], off
	s_waitcnt vmcnt(6)
	s_barrier
	s_setprio 1
	v_mfma_f32_16x16x32_bf16 v[44:47], v[194:197], v[162:165], v[44:47]
	v_mfma_f32_16x16x32_bf16 v[12:15], v[202:205], v[162:165], v[12:15]
	v_mfma_f32_16x16x32_bf16 v[36:39], v[194:197], v[170:173], v[36:39]
	v_mfma_f32_16x16x32_bf16 v[8:11], v[202:205], v[170:173], v[8:11]
	v_mfma_f32_16x16x32_bf16 v[28:31], v[194:197], v[178:181], v[28:31]
	v_mfma_f32_16x16x32_bf16 v[4:7], v[202:205], v[178:181], v[4:7]
	v_mfma_f32_16x16x32_bf16 v[20:23], v[194:197], v[186:189], v[20:23]
	v_mfma_f32_16x16x32_bf16 v[0:3], v[202:205], v[186:189], v[0:3]
	v_mfma_f32_16x16x32_bf16 v[44:47], v[198:201], v[166:169], v[44:47]
	v_mfma_f32_16x16x32_bf16 v[12:15], v[206:209], v[166:169], v[12:15]
	v_mfma_f32_16x16x32_bf16 v[36:39], v[198:201], v[174:177], v[36:39]
	v_mfma_f32_16x16x32_bf16 v[8:11], v[206:209], v[174:177], v[8:11]
	v_mfma_f32_16x16x32_bf16 v[28:31], v[198:201], v[182:185], v[28:31]
	v_mfma_f32_16x16x32_bf16 v[4:7], v[206:209], v[182:185], v[4:7]
	v_mfma_f32_16x16x32_bf16 v[20:23], v[198:201], v[190:193], v[20:23]
	v_mfma_f32_16x16x32_bf16 v[0:3], v[206:209], v[190:193], v[0:3]
	s_setprio 0
	s_add_i32 s42, 0, 0x18000
	v_add_u32_e32 v158, s42, v145
	s_barrier
	ds_read_b128 v[140:143], v158
	ds_read_b128 v[150:153], v158 offset:1024
	ds_read_b128 v[154:157], v158 offset:2048
	ds_read_b128 v[158:161], v158 offset:3072
	s_add_u32 s4, s4, 0x80000
	s_addc_u32 s5, s5, 0
	s_mov_b32 m0, s25
	v_lshl_add_u64 v[194:195], s[4:5], 0, v[130:131]
	ds_read_b128 v[162:165], v148 offset:32768
	ds_read_b128 v[166:169], v148 offset:33792
	ds_read_b128 v[170:173], v148 offset:34816
	ds_read_b128 v[174:177], v148 offset:35840
	ds_read_b128 v[178:181], v148 offset:36864
	ds_read_b128 v[182:185], v148 offset:37888
	ds_read_b128 v[186:189], v148 offset:38912
	ds_read_b128 v[190:193], v148 offset:39936
	global_load_lds_dwordx4 v[194:195], off
	v_lshl_add_u64 v[194:195], s[4:5], 0, v[128:129]
	s_mov_b32 m0, s28
	s_nop 0
	global_load_lds_dwordx4 v[194:195], off
	s_waitcnt lgkmcnt(8)
	s_barrier
	s_waitcnt lgkmcnt(0)
	s_setprio 1
	s_waitcnt lgkmcnt(0)
	v_mfma_f32_16x16x32_bf16 v[124:127], v[140:143], v[162:165], v[124:127]
	v_mfma_f32_16x16x32_bf16 v[100:103], v[154:157], v[162:165], v[100:103]
	v_mfma_f32_16x16x32_bf16 v[120:123], v[140:143], v[170:173], v[120:123]
	v_mfma_f32_16x16x32_bf16 v[96:99], v[154:157], v[170:173], v[96:99]
	v_mfma_f32_16x16x32_bf16 v[116:119], v[140:143], v[178:181], v[116:119]
	v_mfma_f32_16x16x32_bf16 v[88:91], v[154:157], v[178:181], v[88:91]
	v_mfma_f32_16x16x32_bf16 v[112:115], v[140:143], v[186:189], v[112:115]
	v_mfma_f32_16x16x32_bf16 v[80:83], v[154:157], v[186:189], v[80:83]
	v_mfma_f32_16x16x32_bf16 v[124:127], v[150:153], v[166:169], v[124:127]
	v_mfma_f32_16x16x32_bf16 v[100:103], v[158:161], v[166:169], v[100:103]
	v_mfma_f32_16x16x32_bf16 v[120:123], v[150:153], v[174:177], v[120:123]
	v_mfma_f32_16x16x32_bf16 v[96:99], v[158:161], v[174:177], v[96:99]
	v_mfma_f32_16x16x32_bf16 v[116:119], v[150:153], v[182:185], v[116:119]
	v_mfma_f32_16x16x32_bf16 v[88:91], v[158:161], v[182:185], v[88:91]
	v_mfma_f32_16x16x32_bf16 v[112:115], v[150:153], v[190:193], v[112:115]
	v_mfma_f32_16x16x32_bf16 v[80:83], v[158:161], v[190:193], v[80:83]
	s_setprio 0
	s_barrier
	s_add_i32 s43, 0, 0x1c000
	s_add_i32 s4, s42, s21
	v_add_u32_e32 v206, s43, v145
	v_lshl_add_u64 v[210:211], v[210:211], 0, s[16:17]
	s_mov_b32 m0, s4
	ds_read_b128 v[194:197], v206
	ds_read_b128 v[198:201], v206 offset:1024
	ds_read_b128 v[202:205], v206 offset:2048
	ds_read_b128 v[206:209], v206 offset:3072
	global_load_lds_dwordx4 v[210:211], off
	v_lshl_add_u64 v[210:211], v[212:213], 0, s[16:17]
	s_add_i32 m0, s4, 0x2000
	s_nop 0
	global_load_lds_dwordx4 v[210:211], off
	s_barrier
	s_waitcnt lgkmcnt(0)
	s_setprio 1
	s_waitcnt lgkmcnt(0)
	v_mfma_f32_16x16x32_bf16 v[68:71], v[194:197], v[162:165], v[68:71]
	v_mfma_f32_16x16x32_bf16 v[40:43], v[202:205], v[162:165], v[40:43]
	v_mfma_f32_16x16x32_bf16 v[60:63], v[194:197], v[170:173], v[60:63]
	v_mfma_f32_16x16x32_bf16 v[32:35], v[202:205], v[170:173], v[32:35]
	v_mfma_f32_16x16x32_bf16 v[52:55], v[194:197], v[178:181], v[52:55]
	v_mfma_f32_16x16x32_bf16 v[24:27], v[202:205], v[178:181], v[24:27]
	v_mfma_f32_16x16x32_bf16 v[48:51], v[194:197], v[186:189], v[48:51]
	v_mfma_f32_16x16x32_bf16 v[16:19], v[202:205], v[186:189], v[16:19]
	v_mfma_f32_16x16x32_bf16 v[68:71], v[198:201], v[166:169], v[68:71]
	v_mfma_f32_16x16x32_bf16 v[40:43], v[206:209], v[166:169], v[40:43]
	v_mfma_f32_16x16x32_bf16 v[60:63], v[198:201], v[174:177], v[60:63]
	v_mfma_f32_16x16x32_bf16 v[32:35], v[206:209], v[174:177], v[32:35]
	v_mfma_f32_16x16x32_bf16 v[52:55], v[198:201], v[182:185], v[52:55]
	v_mfma_f32_16x16x32_bf16 v[24:27], v[206:209], v[182:185], v[24:27]
	v_mfma_f32_16x16x32_bf16 v[48:51], v[198:201], v[190:193], v[48:51]
	v_mfma_f32_16x16x32_bf16 v[16:19], v[206:209], v[190:193], v[16:19]
	s_setprio 0
	s_mov_b32 m0, s33
	v_lshl_add_u64 v[210:211], v[214:215], 0, s[16:17]
	s_barrier
	ds_read_b128 v[162:165], v148 offset:49152
	ds_read_b128 v[166:169], v148 offset:50176
	ds_read_b128 v[170:173], v148 offset:51200
	ds_read_b128 v[174:177], v148 offset:52224
	ds_read_b128 v[178:181], v148 offset:53248
	ds_read_b128 v[182:185], v148 offset:54272
	ds_read_b128 v[186:189], v148 offset:55296
	ds_read_b128 v[190:193], v148 offset:56320
	global_load_lds_dwordx4 v[210:211], off
	v_lshl_add_u64 v[210:211], v[216:217], 0, s[16:17]
	s_mov_b32 m0, s36
	s_nop 0
	global_load_lds_dwordx4 v[210:211], off
	s_barrier
	s_waitcnt lgkmcnt(0)
	s_setprio 1
	s_waitcnt lgkmcnt(0)
	v_mfma_f32_16x16x32_bf16 v[108:111], v[140:143], v[162:165], v[108:111]
	v_mfma_f32_16x16x32_bf16 v[76:79], v[154:157], v[162:165], v[76:79]
	v_mfma_f32_16x16x32_bf16 v[104:107], v[140:143], v[170:173], v[104:107]
	v_mfma_f32_16x16x32_bf16 v[72:75], v[154:157], v[170:173], v[72:75]
	v_mfma_f32_16x16x32_bf16 v[92:95], v[140:143], v[178:181], v[92:95]
	v_mfma_f32_16x16x32_bf16 v[64:67], v[154:157], v[178:181], v[64:67]
	v_mfma_f32_16x16x32_bf16 v[84:87], v[140:143], v[186:189], v[84:87]
	v_mfma_f32_16x16x32_bf16 v[56:59], v[154:157], v[186:189], v[56:59]
	v_mfma_f32_16x16x32_bf16 v[108:111], v[150:153], v[166:169], v[108:111]
	v_mfma_f32_16x16x32_bf16 v[76:79], v[158:161], v[166:169], v[76:79]
	v_mfma_f32_16x16x32_bf16 v[104:107], v[150:153], v[174:177], v[104:107]
	v_mfma_f32_16x16x32_bf16 v[72:75], v[158:161], v[174:177], v[72:75]
	v_mfma_f32_16x16x32_bf16 v[92:95], v[150:153], v[182:185], v[92:95]
	v_mfma_f32_16x16x32_bf16 v[64:67], v[158:161], v[182:185], v[64:67]
	v_mfma_f32_16x16x32_bf16 v[84:87], v[150:153], v[190:193], v[84:87]
	v_mfma_f32_16x16x32_bf16 v[56:59], v[158:161], v[190:193], v[56:59]
	s_setprio 0
	s_barrier
	s_add_u32 s4, s50, 0x80080
	s_addc_u32 s5, s51, 0
	s_add_i32 s42, s43, s21
	v_lshl_add_u64 v[140:141], s[4:5], 0, v[130:131]
	s_mov_b32 m0, s42
	s_nop 0
	global_load_lds_dwordx4 v[140:141], off
	v_lshl_add_u64 v[140:141], s[4:5], 0, v[128:129]
	s_add_i32 m0, s42, 0x2000
	s_nop 0
	global_load_lds_dwordx4 v[140:141], off
	s_waitcnt vmcnt(6)
	s_barrier
	s_setprio 1
	v_mfma_f32_16x16x32_bf16 v[44:47], v[194:197], v[162:165], v[44:47]
	v_mfma_f32_16x16x32_bf16 v[12:15], v[202:205], v[162:165], v[12:15]
	v_mfma_f32_16x16x32_bf16 v[36:39], v[194:197], v[170:173], v[36:39]
	v_mfma_f32_16x16x32_bf16 v[8:11], v[202:205], v[170:173], v[8:11]
	v_mfma_f32_16x16x32_bf16 v[28:31], v[194:197], v[178:181], v[28:31]
	v_mfma_f32_16x16x32_bf16 v[4:7], v[202:205], v[178:181], v[4:7]
	v_mfma_f32_16x16x32_bf16 v[20:23], v[194:197], v[186:189], v[20:23]
	v_mfma_f32_16x16x32_bf16 v[0:3], v[202:205], v[186:189], v[0:3]
	v_mfma_f32_16x16x32_bf16 v[44:47], v[198:201], v[166:169], v[44:47]
	v_mfma_f32_16x16x32_bf16 v[12:15], v[206:209], v[166:169], v[12:15]
	v_mfma_f32_16x16x32_bf16 v[36:39], v[198:201], v[174:177], v[36:39]
	v_mfma_f32_16x16x32_bf16 v[8:11], v[206:209], v[174:177], v[8:11]
	v_mfma_f32_16x16x32_bf16 v[28:31], v[198:201], v[182:185], v[28:31]
	v_mfma_f32_16x16x32_bf16 v[4:7], v[206:209], v[182:185], v[4:7]
	v_mfma_f32_16x16x32_bf16 v[20:23], v[198:201], v[190:193], v[20:23]
	v_mfma_f32_16x16x32_bf16 v[0:3], v[206:209], v[190:193], v[0:3]
	s_setprio 0
	s_add_i32 s73, s73, 2
	s_add_u32 s61, s61, 0x100
	s_addc_u32 s67, s67, 0
	s_cmp_gt_u32 s73, 29
	s_mov_b64 s[74:75], s[76:77]
	s_barrier
	s_cbranch_scc0 .LBB0_850
	v_lshl_or_b32 v140, s41, 8, v146
	v_lshl_add_u32 v143, s72, 8, v144
	v_lshlrev_b32_e32 v140, 2, v140
	v_lshl_add_u32 v143, v143, 13, v140
	s_mov_b32 s41, s60
	s_mov_b32 s72, s66
	s_mov_b64 s[50:51], s[70:71]
	s_mov_b64 s[74:75], s[68:69]
	v_mov_b32_e32 v141, v143
	v_mov_b32_e32 v142, v143
	global_load_dwordx4 v[166:169], v140, s[14:15] offset:0
	global_load_dwordx4 v[150:153], v141, s[10:11] offset:0
	v_add_u32_e32 v141, 0x20000, v141
	global_load_dwordx4 v[154:157], v141, s[10:11] offset:0
	v_add_u32_e32 v141, 0x20000, v141
	global_load_dwordx4 v[158:161], v141, s[10:11] offset:0
	v_add_u32_e32 v141, 0x20000, v141
	global_load_dwordx4 v[162:165], v141, s[10:11] offset:0
	v_add_u32_e32 v141, 0xa0000, v141
	s_waitcnt vmcnt(3)
	v_pk_fma_f32 v[150:151], v[124:125], v[166:167], v[150:151]
	v_pk_fma_f32 v[152:153], v[126:127], v[168:169], v[152:153]
	global_store_dwordx4 v142, v[150:153], s[12:13] offset:0
	v_add_u32_e32 v142, 0x20000, v142
	global_load_dwordx4 v[150:153], v141, s[10:11] offset:0
	v_add_u32_e32 v141, 0x20000, v141
	s_waitcnt vmcnt(4)
	v_pk_fma_f32 v[154:155], v[120:121], v[166:167], v[154:155]
	v_pk_fma_f32 v[156:157], v[122:123], v[168:169], v[156:157]
	global_store_dwordx4 v142, v[154:157], s[12:13] offset:0
	v_add_u32_e32 v142, 0x20000, v142
	global_load_dwordx4 v[154:157], v141, s[10:11] offset:0
	v_add_u32_e32 v141, 0x20000, v141
	s_waitcnt vmcnt(5)
	v_pk_fma_f32 v[158:159], v[116:117], v[166:167], v[158:159]
	v_pk_fma_f32 v[160:161], v[118:119], v[168:169], v[160:161]
	global_store_dwordx4 v142, v[158:161], s[12:13] offset:0
	v_add_u32_e32 v142, 0x20000, v142
	global_load_dwordx4 v[158:161], v141, s[10:11] offset:0
	v_add_u32_e32 v141, 0x20000, v141
	s_waitcnt vmcnt(6)
	v_pk_fma_f32 v[162:163], v[112:113], v[166:167], v[162:163]
	v_pk_fma_f32 v[164:165], v[114:115], v[168:169], v[164:165]
	global_store_dwordx4 v142, v[162:165], s[12:13] offset:0
	v_add_u32_e32 v142, 0xa0000, v142
	global_load_dwordx4 v[162:165], v141, s[10:11] offset:0
	v_add_u32_e32 v141, 0x20000, v141
	s_waitcnt vmcnt(6)
	v_pk_fma_f32 v[150:151], v[108:109], v[166:167], v[150:151]
	v_pk_fma_f32 v[152:153], v[110:111], v[168:169], v[152:153]
	global_store_dwordx4 v142, v[150:153], s[12:13] offset:0
	v_add_u32_e32 v142, 0x20000, v142
	s_waitcnt vmcnt(5)
	v_pk_fma_f32 v[154:155], v[104:105], v[166:167], v[154:155]
	v_pk_fma_f32 v[156:157], v[106:107], v[168:169], v[156:157]
	global_store_dwordx4 v142, v[154:157], s[12:13] offset:0
	v_add_u32_e32 v142, 0x20000, v142
	s_waitcnt vmcnt(4)
	v_pk_fma_f32 v[158:159], v[92:93], v[166:167], v[158:159]
	v_pk_fma_f32 v[160:161], v[94:95], v[168:169], v[160:161]
	global_store_dwordx4 v142, v[158:161], s[12:13] offset:0
	v_add_u32_e32 v142, 0x20000, v142
	s_waitcnt vmcnt(3)
	v_pk_fma_f32 v[162:163], v[84:85], v[166:167], v[162:163]
	v_pk_fma_f32 v[164:165], v[86:87], v[168:169], v[164:165]
	global_store_dwordx4 v142, v[162:165], s[12:13] offset:0
	v_add_u32_e32 v142, 0x20000, v142
	v_mov_b32_e32 v141, v143
	v_mov_b32_e32 v142, v143
	global_load_dwordx4 v[166:169], v140, s[14:15] offset:64
	global_load_dwordx4 v[150:153], v141, s[10:11] offset:64
	v_add_u32_e32 v141, 0x20000, v141
	global_load_dwordx4 v[154:157], v141, s[10:11] offset:64
	v_add_u32_e32 v141, 0x20000, v141
	global_load_dwordx4 v[158:161], v141, s[10:11] offset:64
	v_add_u32_e32 v141, 0x20000, v141
	global_load_dwordx4 v[162:165], v141, s[10:11] offset:64
	v_add_u32_e32 v141, 0xa0000, v141
	s_waitcnt vmcnt(3)
	v_pk_fma_f32 v[150:151], v[100:101], v[166:167], v[150:151]
	v_pk_fma_f32 v[152:153], v[102:103], v[168:169], v[152:153]
	global_store_dwordx4 v142, v[150:153], s[12:13] offset:64
	v_add_u32_e32 v142, 0x20000, v142
	global_load_dwordx4 v[150:153], v141, s[10:11] offset:64
	v_add_u32_e32 v141, 0x20000, v141
	s_waitcnt vmcnt(4)
	v_pk_fma_f32 v[154:155], v[96:97], v[166:167], v[154:155]
	v_pk_fma_f32 v[156:157], v[98:99], v[168:169], v[156:157]
	global_store_dwordx4 v142, v[154:157], s[12:13] offset:64
	v_add_u32_e32 v142, 0x20000, v142
	global_load_dwordx4 v[154:157], v141, s[10:11] offset:64
	v_add_u32_e32 v141, 0x20000, v141
	s_waitcnt vmcnt(5)
	v_pk_fma_f32 v[158:159], v[88:89], v[166:167], v[158:159]
	v_pk_fma_f32 v[160:161], v[90:91], v[168:169], v[160:161]
	global_store_dwordx4 v142, v[158:161], s[12:13] offset:64
	v_add_u32_e32 v142, 0x20000, v142
	global_load_dwordx4 v[158:161], v141, s[10:11] offset:64
	v_add_u32_e32 v141, 0x20000, v141
	s_waitcnt vmcnt(6)
	v_pk_fma_f32 v[162:163], v[80:81], v[166:167], v[162:163]
	v_pk_fma_f32 v[164:165], v[82:83], v[168:169], v[164:165]
	global_store_dwordx4 v142, v[162:165], s[12:13] offset:64
	v_add_u32_e32 v142, 0xa0000, v142
	global_load_dwordx4 v[162:165], v141, s[10:11] offset:64
	v_add_u32_e32 v141, 0x20000, v141
	s_waitcnt vmcnt(6)
	v_pk_fma_f32 v[150:151], v[76:77], v[166:167], v[150:151]
	v_pk_fma_f32 v[152:153], v[78:79], v[168:169], v[152:153]
	global_store_dwordx4 v142, v[150:153], s[12:13] offset:64
	v_add_u32_e32 v142, 0x20000, v142
	s_waitcnt vmcnt(5)
	v_pk_fma_f32 v[154:155], v[72:73], v[166:167], v[154:155]
	v_pk_fma_f32 v[156:157], v[74:75], v[168:169], v[156:157]
	global_store_dwordx4 v142, v[154:157], s[12:13] offset:64
	v_add_u32_e32 v142, 0x20000, v142
	s_waitcnt vmcnt(4)
	v_pk_fma_f32 v[158:159], v[64:65], v[166:167], v[158:159]
	v_pk_fma_f32 v[160:161], v[66:67], v[168:169], v[160:161]
	global_store_dwordx4 v142, v[158:161], s[12:13] offset:64
	v_add_u32_e32 v142, 0x20000, v142
	s_waitcnt vmcnt(3)
	v_pk_fma_f32 v[162:163], v[56:57], v[166:167], v[162:163]
	v_pk_fma_f32 v[164:165], v[58:59], v[168:169], v[164:165]
	global_store_dwordx4 v142, v[162:165], s[12:13] offset:64
	v_add_u32_e32 v142, 0x20000, v142
	v_mov_b32_e32 v141, v143
	v_mov_b32_e32 v142, v143
	global_load_dwordx4 v[166:169], v140, s[14:15] offset:512
	global_load_dwordx4 v[150:153], v141, s[10:11] offset:512
	v_add_u32_e32 v141, 0x20000, v141
	global_load_dwordx4 v[154:157], v141, s[10:11] offset:512
	v_add_u32_e32 v141, 0x20000, v141
	global_load_dwordx4 v[158:161], v141, s[10:11] offset:512
	v_add_u32_e32 v141, 0x20000, v141
	global_load_dwordx4 v[162:165], v141, s[10:11] offset:512
	v_add_u32_e32 v141, 0xa0000, v141
	s_waitcnt vmcnt(3)
	v_pk_fma_f32 v[150:151], v[68:69], v[166:167], v[150:151]
	v_pk_fma_f32 v[152:153], v[70:71], v[168:169], v[152:153]
	global_store_dwordx4 v142, v[150:153], s[12:13] offset:512
	v_add_u32_e32 v142, 0x20000, v142
	global_load_dwordx4 v[150:153], v141, s[10:11] offset:512
	v_add_u32_e32 v141, 0x20000, v141
	s_waitcnt vmcnt(4)
	v_pk_fma_f32 v[154:155], v[60:61], v[166:167], v[154:155]
	v_pk_fma_f32 v[156:157], v[62:63], v[168:169], v[156:157]
	global_store_dwordx4 v142, v[154:157], s[12:13] offset:512
	v_add_u32_e32 v142, 0x20000, v142
	global_load_dwordx4 v[154:157], v141, s[10:11] offset:512
	v_add_u32_e32 v141, 0x20000, v141
	s_waitcnt vmcnt(5)
	v_pk_fma_f32 v[158:159], v[52:53], v[166:167], v[158:159]
	v_pk_fma_f32 v[160:161], v[54:55], v[168:169], v[160:161]
	global_store_dwordx4 v142, v[158:161], s[12:13] offset:512
	v_add_u32_e32 v142, 0x20000, v142
	global_load_dwordx4 v[158:161], v141, s[10:11] offset:512
	v_add_u32_e32 v141, 0x20000, v141
	s_waitcnt vmcnt(6)
	v_pk_fma_f32 v[162:163], v[48:49], v[166:167], v[162:163]
	v_pk_fma_f32 v[164:165], v[50:51], v[168:169], v[164:165]
	global_store_dwordx4 v142, v[162:165], s[12:13] offset:512
	v_add_u32_e32 v142, 0xa0000, v142
	global_load_dwordx4 v[162:165], v141, s[10:11] offset:512
	v_add_u32_e32 v141, 0x20000, v141
	s_waitcnt vmcnt(6)
	v_pk_fma_f32 v[150:151], v[44:45], v[166:167], v[150:151]
	v_pk_fma_f32 v[152:153], v[46:47], v[168:169], v[152:153]
	global_store_dwordx4 v142, v[150:153], s[12:13] offset:512
	v_add_u32_e32 v142, 0x20000, v142
	s_waitcnt vmcnt(5)
	v_pk_fma_f32 v[154:155], v[36:37], v[166:167], v[154:155]
	v_pk_fma_f32 v[156:157], v[38:39], v[168:169], v[156:157]
	global_store_dwordx4 v142, v[154:157], s[12:13] offset:512
	v_add_u32_e32 v142, 0x20000, v142
	s_waitcnt vmcnt(4)
	v_pk_fma_f32 v[158:159], v[28:29], v[166:167], v[158:159]
	v_pk_fma_f32 v[160:161], v[30:31], v[168:169], v[160:161]
	global_store_dwordx4 v142, v[158:161], s[12:13] offset:512
	v_add_u32_e32 v142, 0x20000, v142
	s_waitcnt vmcnt(3)
	v_pk_fma_f32 v[162:163], v[20:21], v[166:167], v[162:163]
	v_pk_fma_f32 v[164:165], v[22:23], v[168:169], v[164:165]
	global_store_dwordx4 v142, v[162:165], s[12:13] offset:512
	v_add_u32_e32 v142, 0x20000, v142
	v_mov_b32_e32 v141, v143
	v_mov_b32_e32 v142, v143
	global_load_dwordx4 v[166:169], v140, s[14:15] offset:576
	global_load_dwordx4 v[150:153], v141, s[10:11] offset:576
	v_add_u32_e32 v141, 0x20000, v141
	global_load_dwordx4 v[154:157], v141, s[10:11] offset:576
	v_add_u32_e32 v141, 0x20000, v141
	global_load_dwordx4 v[158:161], v141, s[10:11] offset:576
	v_add_u32_e32 v141, 0x20000, v141
	global_load_dwordx4 v[162:165], v141, s[10:11] offset:576
	v_add_u32_e32 v141, 0xa0000, v141
	s_waitcnt vmcnt(3)
	v_pk_fma_f32 v[150:151], v[40:41], v[166:167], v[150:151]
	v_pk_fma_f32 v[152:153], v[42:43], v[168:169], v[152:153]
	global_store_dwordx4 v142, v[150:153], s[12:13] offset:576
	v_add_u32_e32 v142, 0x20000, v142
	global_load_dwordx4 v[150:153], v141, s[10:11] offset:576
	v_add_u32_e32 v141, 0x20000, v141
	s_waitcnt vmcnt(4)
	v_pk_fma_f32 v[154:155], v[32:33], v[166:167], v[154:155]
	v_pk_fma_f32 v[156:157], v[34:35], v[168:169], v[156:157]
	global_store_dwordx4 v142, v[154:157], s[12:13] offset:576
	v_add_u32_e32 v142, 0x20000, v142
	global_load_dwordx4 v[154:157], v141, s[10:11] offset:576
	v_add_u32_e32 v141, 0x20000, v141
	s_waitcnt vmcnt(5)
	v_pk_fma_f32 v[158:159], v[24:25], v[166:167], v[158:159]
	v_pk_fma_f32 v[160:161], v[26:27], v[168:169], v[160:161]
	global_store_dwordx4 v142, v[158:161], s[12:13] offset:576
	v_add_u32_e32 v142, 0x20000, v142
	global_load_dwordx4 v[158:161], v141, s[10:11] offset:576
	v_add_u32_e32 v141, 0x20000, v141
	s_waitcnt vmcnt(6)
	v_pk_fma_f32 v[162:163], v[16:17], v[166:167], v[162:163]
	v_pk_fma_f32 v[164:165], v[18:19], v[168:169], v[164:165]
	global_store_dwordx4 v142, v[162:165], s[12:13] offset:576
	v_add_u32_e32 v142, 0xa0000, v142
	global_load_dwordx4 v[162:165], v141, s[10:11] offset:576
	v_add_u32_e32 v141, 0x20000, v141
	s_waitcnt vmcnt(6)
	v_pk_fma_f32 v[150:151], v[12:13], v[166:167], v[150:151]
	v_pk_fma_f32 v[152:153], v[14:15], v[168:169], v[152:153]
	global_store_dwordx4 v142, v[150:153], s[12:13] offset:576
	v_add_u32_e32 v142, 0x20000, v142
	s_waitcnt vmcnt(5)
	v_pk_fma_f32 v[154:155], v[8:9], v[166:167], v[154:155]
	v_pk_fma_f32 v[156:157], v[10:11], v[168:169], v[156:157]
	global_store_dwordx4 v142, v[154:157], s[12:13] offset:576
	v_add_u32_e32 v142, 0x20000, v142
	s_waitcnt vmcnt(4)
	v_pk_fma_f32 v[158:159], v[4:5], v[166:167], v[158:159]
	v_pk_fma_f32 v[160:161], v[6:7], v[168:169], v[160:161]
	global_store_dwordx4 v142, v[158:161], s[12:13] offset:576
	v_add_u32_e32 v142, 0x20000, v142
	s_waitcnt vmcnt(3)
	v_pk_fma_f32 v[162:163], v[0:1], v[166:167], v[162:163]
	v_pk_fma_f32 v[164:165], v[2:3], v[168:169], v[164:165]
	global_store_dwordx4 v142, v[162:165], s[12:13] offset:576
	v_add_u32_e32 v142, 0x20000, v142
	s_and_b64 vcc, exec, s[6:7]
	s_cbranch_vccz .LBB0_843
	s_waitcnt vmcnt(0)
	s_cmpk_gt_u32 s20, 0xff
	s_cbranch_scc1 .LBB0_854
	s_barrier
